# P2 v tiles: g_v slice loaded one float per lane before the K-loop, epilogue distributes with ds_bpermute (no vmcnt(0) stall in the v epilogue)
# baseline (speedup 1.0000x reference)
;     __device__ __forceinline__ void row(const f32x4 (&a)[2][2], int row, int pn, int wc, int fq) const {
;     ...
;                 const f32x4 v0 = g[bj][0] * rs * *(const f32x4*)(g_v + d), v1 = g[bj][1] * rs * *(const f32x4*)(g_v + d + 4);
; template <class Epi>
; __device__ __forceinline__ void gemm_phase(LAS unsigned char* lds, const Gemm g, const StaticOrder& S, const Epi& E, float* smem = nullptr) {
;     ...
;     for (;;) {
;         const bool has_next = S.next(ui + 1, nxt);
;         const char* nA = has_next ? (const char*)g.A + (size_t)nxt.pm * tstep : cA; const char* nB = has_next ? (const char*)g.Bt + (size_t)nxt.pn * tstep : cB;
;         for (int t = 0; t < nt; t += 2) {
.LBB0_211:
	s_and_b32 s98, s0, -2
	s_cmp_lg_u32 s98, 2
	s_cbranch_scc1 .Lgv_skip
	v_mbcnt_lo_u32_b32 v241, -1, 0
	v_mbcnt_hi_u32_b32 v241, -1, v241
	v_add_u32_e32 v241, v241, v184
	v_sub_u32_e32 v241, v241, v142
	v_lshl_add_u32 v241, s0, 8, v241
	v_lshlrev_b32_e32 v241, 2, v241
	global_load_dword v241, v241, s[18:19]

; #define PG8_STAGE(bufoff, gbase, voff) do { _Pragma("unroll") for (int _i = 0; _i < 2; ++_i) \
;         __builtin_amdgcn_global_load_lds((const unsigned*)((const char*)(gbase) + (voff)[_i]), (LAS unsigned*)(lds + (bufoff) + ldsw + _i * 8192), 16, 0, 0); } while (0)
; #define PG8_LDA(dst, b, h) do { _Pragma("unroll") for (int m = 0; m < 4; ++m) _Pragma("unroll") for (int k = 0; k < 2; ++k) dst[m][k] = *(const LAS bf16x8*)(lds + PG8_SA(b, h) + aoff + m * 2048 + k * 1024); } while (0)
; #define PG8_LDB(dst, b, h) do { _Pragma("unroll") for (int n = 0; n < 2; ++n) _Pragma("unroll") for (int k = 0; k < 2; ++k) dst[n][k] = *(const LAS bf16x8*)(lds + PG8_SB(b, h) + boff + n * 2048 + k * 1024); } while (0)
; #define PG8_MMA(ai, bj, At, Bt) do { __builtin_amdgcn_s_setprio(1); _Pragma("unroll") for (int m = 0; m < 4; ++m) _Pragma("unroll") for (int n = 0; n < 2; ++n) _Pragma("unroll") for (int k = 0; k < 2; ++k) \
;         acc[ai][bj][m][n] = __builtin_amdgcn_mfma_f32_16x16x32_bf16(Bt[n][k], At[m][k], acc[ai][bj][m][n], 0, 0, 0); __builtin_amdgcn_s_setprio(0); } while (0)
; #define PG8_WAIT_V(n) asm volatile("s_waitcnt vmcnt(" #n ")" ::: "memory")
; #define PG8_WAIT_L(n) asm volatile("s_waitcnt lgkmcnt(" #n ")" ::: "memory")
; #define PG8_BAR __builtin_amdgcn_s_barrier()
; #define PG8_SCHED __builtin_amdgcn_sched_barrier(0)
; template <class Epi>
; __device__ __forceinline__ void gemm_phase(LAS unsigned char* lds, const Gemm g, const StaticOrder& S, const Epi& E, float* smem = nullptr) {
;     ...
;             PG8_LDB(B0, 0, 0); PG8_SCHED; PG8_LDA(At, 0, 0); PG8_STAGE(PG8_SA(1, 1), a1 + hstep, voffA);
;             PG8_WAIT_L(8); PG8_BAR; PG8_WAIT_L(0); PG8_MMA(0, 0, At, B0); PG8_BAR; PG8_SCHED;
;             PG8_LDB(B1, 0, 1); PG8_STAGE(PG8_SB(0, 0), b2, voffA);
;             PG8_BAR; PG8_WAIT_L(0); PG8_MMA(0, 1, At, B1); PG8_BAR;
;             PG8_LDA(At, 0, 1); PG8_STAGE(PG8_SA(0, 0), a2, voffA);
;             PG8_BAR; PG8_WAIT_L(0); PG8_MMA(1, 0, At, B0); PG8_BAR; PG8_SCHED;
;             PG8_STAGE(PG8_SB(0, 1), b2 + hstep, voffA);
;             PG8_WAIT_V(6); PG8_BAR; PG8_MMA(1, 1, At, B1); PG8_BAR;
.LBB0_212:
	ds_read_b128 v[128:131], v185
	ds_read_b128 v[132:135], v185 offset:1024
	ds_read_b128 v[152:155], v185 offset:2048
	ds_read_b128 v[156:159], v185 offset:3072
	s_add_u32 s8, s6, 0xfffc0080
	s_addc_u32 s9, s7, -1
	s_cmp_eq_u32 s80, 12
	s_cselect_b32 s11, s1, s9
	s_cselect_b32 s10, s5, s8
	s_cselect_b32 s9, s61, s75
	s_cselect_b32 s8, s64, s73
	v_lshl_add_u64 v[180:181], s[6:7], 0, v[144:145]
	s_add_i32 m0, s86, 0xc000
	ds_read_b128 v[160:163], v186
	ds_read_b128 v[164:167], v186 offset:1024
	ds_read_b128 v[168:171], v186 offset:2048
	ds_read_b128 v[172:175], v186 offset:3072
	ds_read_b128 v[176:179], v186 offset:4096
	ds_read_b128 v[190:193], v186 offset:5120
	ds_read_b128 v[194:197], v186 offset:6144
	ds_read_b128 v[198:201], v186 offset:7168
	global_load_lds_dwordx4 v[180:181], off
	v_lshl_add_u64 v[180:181], s[6:7], 0, v[146:147]
	s_add_i32 m0, s86, 0xe000
	s_nop 0
	global_load_lds_dwordx4 v[180:181], off
	s_waitcnt lgkmcnt(8)
	s_barrier
	s_waitcnt lgkmcnt(0)
	s_waitcnt lgkmcnt(0)
	v_mfma_f32_16x16x32_bf16 v[124:127], v[128:131], v[160:163], v[124:127]
	v_mfma_f32_16x16x32_bf16 v[120:123], v[152:155], v[160:163], v[120:123]
	v_mfma_f32_16x16x32_bf16 v[108:111], v[128:131], v[168:171], v[108:111]
	v_mfma_f32_16x16x32_bf16 v[104:107], v[152:155], v[168:171], v[104:107]
	v_mfma_f32_16x16x32_bf16 v[92:95], v[128:131], v[176:179], v[92:95]
	v_mfma_f32_16x16x32_bf16 v[88:91], v[152:155], v[176:179], v[88:91]
	v_mfma_f32_16x16x32_bf16 v[76:79], v[128:131], v[194:197], v[76:79]
	v_mfma_f32_16x16x32_bf16 v[72:75], v[152:155], v[194:197], v[72:75]
	v_mfma_f32_16x16x32_bf16 v[124:127], v[132:135], v[164:167], v[124:127]
	v_mfma_f32_16x16x32_bf16 v[120:123], v[156:159], v[164:167], v[120:123]
	v_mfma_f32_16x16x32_bf16 v[108:111], v[132:135], v[172:175], v[108:111]
	v_mfma_f32_16x16x32_bf16 v[104:107], v[156:159], v[172:175], v[104:107]
	v_mfma_f32_16x16x32_bf16 v[92:95], v[132:135], v[190:193], v[92:95]
	v_mfma_f32_16x16x32_bf16 v[88:91], v[156:159], v[190:193], v[88:91]
	v_mfma_f32_16x16x32_bf16 v[76:79], v[132:135], v[198:201], v[76:79]
	v_mfma_f32_16x16x32_bf16 v[72:75], v[156:159], v[198:201], v[72:75]
	s_barrier
	s_add_i32 s81, s84, s85
	v_lshl_add_u64 v[180:181], s[8:9], 0, v[136:137]
	s_mov_b32 m0, s81
	ds_read_b128 v[202:205], v187
	ds_read_b128 v[206:209], v187 offset:1024
	ds_read_b128 v[210:213], v187 offset:2048
	ds_read_b128 v[214:217], v187 offset:3072
	global_load_lds_dwordx4 v[180:181], off
	v_lshl_add_u64 v[218:219], s[8:9], 0, v[138:139]
	s_add_i32 m0, s81, 0x2000
	s_nop 0
	global_load_lds_dwordx4 v[218:219], off
	s_barrier
	s_waitcnt lgkmcnt(0)
	s_waitcnt lgkmcnt(0)
	v_mfma_f32_16x16x32_bf16 v[116:119], v[202:205], v[160:163], v[116:119]
	v_mfma_f32_16x16x32_bf16 v[112:115], v[210:213], v[160:163], v[112:115]
	v_mfma_f32_16x16x32_bf16 v[100:103], v[202:205], v[168:171], v[100:103]
	v_mfma_f32_16x16x32_bf16 v[96:99], v[210:213], v[168:171], v[96:99]
	v_mfma_f32_16x16x32_bf16 v[84:87], v[202:205], v[176:179], v[84:87]
	v_mfma_f32_16x16x32_bf16 v[80:83], v[210:213], v[176:179], v[80:83]
	v_mfma_f32_16x16x32_bf16 v[68:71], v[202:205], v[194:197], v[68:71]
	v_mfma_f32_16x16x32_bf16 v[64:67], v[210:213], v[194:197], v[64:67]
	v_mfma_f32_16x16x32_bf16 v[116:119], v[206:209], v[164:167], v[116:119]
	v_mfma_f32_16x16x32_bf16 v[112:115], v[214:217], v[164:167], v[112:115]
	v_mfma_f32_16x16x32_bf16 v[100:103], v[206:209], v[172:175], v[100:103]
	v_mfma_f32_16x16x32_bf16 v[96:99], v[214:217], v[172:175], v[96:99]
	v_mfma_f32_16x16x32_bf16 v[84:87], v[206:209], v[190:193], v[84:87]
	v_mfma_f32_16x16x32_bf16 v[80:83], v[214:217], v[190:193], v[80:83]
	v_mfma_f32_16x16x32_bf16 v[68:71], v[206:209], v[198:201], v[68:71]
	v_mfma_f32_16x16x32_bf16 v[64:67], v[214:217], v[198:201], v[64:67]
	s_mov_b32 m0, s86
	v_lshl_add_u64 v[220:221], s[10:11], 0, v[136:137]
	s_barrier
	ds_read_b128 v[160:163], v186 offset:16384
	ds_read_b128 v[164:167], v186 offset:17408
	ds_read_b128 v[168:171], v186 offset:18432
	ds_read_b128 v[172:175], v186 offset:19456
	ds_read_b128 v[176:179], v186 offset:20480
	ds_read_b128 v[190:193], v186 offset:21504
	ds_read_b128 v[194:197], v186 offset:22528
	ds_read_b128 v[198:201], v186 offset:23552
	global_load_lds_dwordx4 v[220:221], off
	v_lshl_add_u64 v[222:223], s[10:11], 0, v[138:139]
	s_mov_b32 m0, s87
	s_nop 0
	global_load_lds_dwordx4 v[222:223], off
	s_barrier
	s_waitcnt lgkmcnt(0)
	s_waitcnt lgkmcnt(0)
	v_mfma_f32_16x16x32_bf16 v[60:63], v[128:131], v[160:163], v[60:63]
	v_mfma_f32_16x16x32_bf16 v[56:59], v[152:155], v[160:163], v[56:59]
	v_mfma_f32_16x16x32_bf16 v[44:47], v[128:131], v[168:171], v[44:47]
	v_mfma_f32_16x16x32_bf16 v[40:43], v[152:155], v[168:171], v[40:43]
	v_mfma_f32_16x16x32_bf16 v[28:31], v[128:131], v[176:179], v[28:31]
	v_mfma_f32_16x16x32_bf16 v[24:27], v[152:155], v[176:179], v[24:27]
	v_mfma_f32_16x16x32_bf16 v[12:15], v[128:131], v[194:197], v[12:15]
	v_mfma_f32_16x16x32_bf16 v[8:11], v[152:155], v[194:197], v[8:11]
	v_mfma_f32_16x16x32_bf16 v[60:63], v[132:135], v[164:167], v[60:63]
	v_mfma_f32_16x16x32_bf16 v[56:59], v[156:159], v[164:167], v[56:59]
	v_mfma_f32_16x16x32_bf16 v[44:47], v[132:135], v[172:175], v[44:47]
	v_mfma_f32_16x16x32_bf16 v[40:43], v[156:159], v[172:175], v[40:43]
	v_mfma_f32_16x16x32_bf16 v[28:31], v[132:135], v[190:193], v[28:31]
	v_mfma_f32_16x16x32_bf16 v[24:27], v[156:159], v[190:193], v[24:27]
	v_mfma_f32_16x16x32_bf16 v[12:15], v[132:135], v[198:201], v[12:15]
	v_mfma_f32_16x16x32_bf16 v[8:11], v[156:159], v[198:201], v[8:11]
	s_barrier
; #define PG8_STAGE(bufoff, gbase, voff) do { _Pragma("unroll") for (int _i = 0; _i < 2; ++_i) \
;         __builtin_amdgcn_global_load_lds((const unsigned*)((const char*)(gbase) + (voff)[_i]), (LAS unsigned*)(lds + (bufoff) + ldsw + _i * 8192), 16, 0, 0); } while (0)
; #define PG8_LDA(dst, b, h) do { _Pragma("unroll") for (int m = 0; m < 4; ++m) _Pragma("unroll") for (int k = 0; k < 2; ++k) dst[m][k] = *(const LAS bf16x8*)(lds + PG8_SA(b, h) + aoff + m * 2048 + k * 1024); } while (0)
; #define PG8_LDB(dst, b, h) do { _Pragma("unroll") for (int n = 0; n < 2; ++n) _Pragma("unroll") for (int k = 0; k < 2; ++k) dst[n][k] = *(const LAS bf16x8*)(lds + PG8_SB(b, h) + boff + n * 2048 + k * 1024); } while (0)
; #define PG8_MMA(ai, bj, At, Bt) do { __builtin_amdgcn_s_setprio(1); _Pragma("unroll") for (int m = 0; m < 4; ++m) _Pragma("unroll") for (int n = 0; n < 2; ++n) _Pragma("unroll") for (int k = 0; k < 2; ++k) \
;         acc[ai][bj][m][n] = __builtin_amdgcn_mfma_f32_16x16x32_bf16(Bt[n][k], At[m][k], acc[ai][bj][m][n], 0, 0, 0); __builtin_amdgcn_s_setprio(0); } while (0)
; #define PG8_WAIT_V(n) asm volatile("s_waitcnt vmcnt(" #n ")" ::: "memory")
; #define PG8_WAIT_L(n) asm volatile("s_waitcnt lgkmcnt(" #n ")" ::: "memory")
; #define PG8_BAR __builtin_amdgcn_s_barrier()
; #define PG8_SCHED __builtin_amdgcn_sched_barrier(0)
; template <class Epi>
; __device__ __forceinline__ void gemm_phase(LAS unsigned char* lds, const Gemm g, const StaticOrder& S, const Epi& E, float* smem = nullptr) {
;     ...
;             PG8_WAIT_V(6); PG8_BAR; PG8_MMA(1, 1, At, B1); PG8_BAR;
;             PG8_LDB(B0, 1, 0); PG8_SCHED; PG8_LDA(At, 1, 0); PG8_STAGE(PG8_SA(0, 1), a2 + hstep, voffA);
;             PG8_WAIT_L(8); PG8_BAR; PG8_WAIT_L(0); PG8_MMA(0, 0, At, B0); PG8_BAR; PG8_SCHED;
;             PG8_LDB(B1, 1, 1); PG8_STAGE(PG8_SB(1, 0), b3, voffA);
;             PG8_BAR; PG8_WAIT_L(0); PG8_MMA(0, 1, At, B1); PG8_BAR;
;             PG8_LDA(At, 1, 1); PG8_STAGE(PG8_SA(1, 0), a3, voffA);
;             PG8_BAR; PG8_WAIT_L(0); PG8_MMA(1, 0, At, B0); PG8_BAR; PG8_SCHED;
	s_add_u32 s82, s8, 0x40000
	s_addc_u32 s83, s9, 0
	s_add_i32 s81, s33, s85
	v_lshl_add_u64 v[128:129], s[82:83], 0, v[136:137]
	s_mov_b32 m0, s81
	s_nop 0
	global_load_lds_dwordx4 v[128:129], off
	v_lshl_add_u64 v[128:129], s[82:83], 0, v[138:139]
	s_add_i32 m0, s81, 0x2000
	s_nop 0
	global_load_lds_dwordx4 v[128:129], off
	s_waitcnt vmcnt(6)
	s_barrier
	v_mfma_f32_16x16x32_bf16 v[52:55], v[202:205], v[160:163], v[52:55]
	v_mfma_f32_16x16x32_bf16 v[48:51], v[210:213], v[160:163], v[48:51]
	v_mfma_f32_16x16x32_bf16 v[36:39], v[202:205], v[168:171], v[36:39]
	v_mfma_f32_16x16x32_bf16 v[32:35], v[210:213], v[168:171], v[32:35]
	v_mfma_f32_16x16x32_bf16 v[20:23], v[202:205], v[176:179], v[20:23]
	v_mfma_f32_16x16x32_bf16 v[16:19], v[210:213], v[176:179], v[16:19]
	v_mfma_f32_16x16x32_bf16 v[4:7], v[202:205], v[194:197], v[4:7]
	v_mfma_f32_16x16x32_bf16 v[0:3], v[210:213], v[194:197], v[0:3]
	v_mfma_f32_16x16x32_bf16 v[52:55], v[206:209], v[164:167], v[52:55]
	v_mfma_f32_16x16x32_bf16 v[48:51], v[214:217], v[164:167], v[48:51]
	v_mfma_f32_16x16x32_bf16 v[36:39], v[206:209], v[172:175], v[36:39]
	v_mfma_f32_16x16x32_bf16 v[32:35], v[214:217], v[172:175], v[32:35]
	v_mfma_f32_16x16x32_bf16 v[20:23], v[206:209], v[190:193], v[20:23]
	v_mfma_f32_16x16x32_bf16 v[16:19], v[214:217], v[190:193], v[16:19]
	v_mfma_f32_16x16x32_bf16 v[4:7], v[206:209], v[198:201], v[4:7]
	v_mfma_f32_16x16x32_bf16 v[0:3], v[214:217], v[198:201], v[0:3]
	s_add_i32 s81, 16, 0x18000
	v_add_u32_e32 v140, s81, v182
	s_barrier
	ds_read_b128 v[128:131], v140
	ds_read_b128 v[132:135], v140 offset:1024
	ds_read_b128 v[152:155], v140 offset:2048
	ds_read_b128 v[156:159], v140 offset:3072
	s_add_u32 s10, s10, 0x40000
	s_addc_u32 s11, s11, 0
	s_mov_b32 m0, s88
	v_lshl_add_u64 v[202:203], s[10:11], 0, v[136:137]
	ds_read_b128 v[160:163], v186 offset:32768
	ds_read_b128 v[164:167], v186 offset:33792
	ds_read_b128 v[168:171], v186 offset:34816
	ds_read_b128 v[172:175], v186 offset:35840
	ds_read_b128 v[176:179], v186 offset:36864
	ds_read_b128 v[190:193], v186 offset:37888
	ds_read_b128 v[194:197], v186 offset:38912
	ds_read_b128 v[198:201], v186 offset:39936
	global_load_lds_dwordx4 v[202:203], off
	v_lshl_add_u64 v[202:203], s[10:11], 0, v[138:139]
	s_mov_b32 m0, s89
	s_nop 0
	global_load_lds_dwordx4 v[202:203], off
	s_waitcnt lgkmcnt(8)
	s_barrier
	s_waitcnt lgkmcnt(0)
	s_waitcnt lgkmcnt(0)
	v_mfma_f32_16x16x32_bf16 v[124:127], v[128:131], v[160:163], v[124:127]
	v_mfma_f32_16x16x32_bf16 v[120:123], v[152:155], v[160:163], v[120:123]
	v_mfma_f32_16x16x32_bf16 v[108:111], v[128:131], v[168:171], v[108:111]
	v_mfma_f32_16x16x32_bf16 v[104:107], v[152:155], v[168:171], v[104:107]
	v_mfma_f32_16x16x32_bf16 v[92:95], v[128:131], v[176:179], v[92:95]
	v_mfma_f32_16x16x32_bf16 v[88:91], v[152:155], v[176:179], v[88:91]
	v_mfma_f32_16x16x32_bf16 v[76:79], v[128:131], v[194:197], v[76:79]
	v_mfma_f32_16x16x32_bf16 v[72:75], v[152:155], v[194:197], v[72:75]
	v_mfma_f32_16x16x32_bf16 v[124:127], v[132:135], v[164:167], v[124:127]
	v_mfma_f32_16x16x32_bf16 v[120:123], v[156:159], v[164:167], v[120:123]
	v_mfma_f32_16x16x32_bf16 v[108:111], v[132:135], v[172:175], v[108:111]
	v_mfma_f32_16x16x32_bf16 v[104:107], v[156:159], v[172:175], v[104:107]
	v_mfma_f32_16x16x32_bf16 v[92:95], v[132:135], v[190:193], v[92:95]
	v_mfma_f32_16x16x32_bf16 v[88:91], v[156:159], v[190:193], v[88:91]
	v_mfma_f32_16x16x32_bf16 v[76:79], v[132:135], v[198:201], v[76:79]
	v_mfma_f32_16x16x32_bf16 v[72:75], v[156:159], v[198:201], v[72:75]
	s_barrier
	s_add_i32 s10, 16, 0x1c000
	s_add_i32 s11, s81, s85
	v_add_u32_e32 v140, s10, v182
	v_lshl_add_u64 v[180:181], v[180:181], 0, s[52:53]
	s_mov_b32 m0, s11
	ds_read_b128 v[202:205], v140
	ds_read_b128 v[206:209], v140 offset:1024
	ds_read_b128 v[210:213], v140 offset:2048
	ds_read_b128 v[214:217], v140 offset:3072
	global_load_lds_dwordx4 v[180:181], off
	v_lshl_add_u64 v[180:181], v[218:219], 0, s[52:53]
	s_add_i32 m0, s11, 0x2000
	s_nop 0
	global_load_lds_dwordx4 v[180:181], off
	s_barrier
	s_waitcnt lgkmcnt(0)
	s_waitcnt lgkmcnt(0)
	v_mfma_f32_16x16x32_bf16 v[116:119], v[202:205], v[160:163], v[116:119]
	v_mfma_f32_16x16x32_bf16 v[112:115], v[210:213], v[160:163], v[112:115]
	v_mfma_f32_16x16x32_bf16 v[100:103], v[202:205], v[168:171], v[100:103]
	v_mfma_f32_16x16x32_bf16 v[96:99], v[210:213], v[168:171], v[96:99]
	v_mfma_f32_16x16x32_bf16 v[84:87], v[202:205], v[176:179], v[84:87]
	v_mfma_f32_16x16x32_bf16 v[80:83], v[210:213], v[176:179], v[80:83]
	v_mfma_f32_16x16x32_bf16 v[68:71], v[202:205], v[194:197], v[68:71]
	v_mfma_f32_16x16x32_bf16 v[64:67], v[210:213], v[194:197], v[64:67]
	v_mfma_f32_16x16x32_bf16 v[116:119], v[206:209], v[164:167], v[116:119]
	v_mfma_f32_16x16x32_bf16 v[112:115], v[214:217], v[164:167], v[112:115]
	v_mfma_f32_16x16x32_bf16 v[100:103], v[206:209], v[172:175], v[100:103]
	v_mfma_f32_16x16x32_bf16 v[96:99], v[214:217], v[172:175], v[96:99]
	v_mfma_f32_16x16x32_bf16 v[84:87], v[206:209], v[190:193], v[84:87]
	v_mfma_f32_16x16x32_bf16 v[80:83], v[214:217], v[190:193], v[80:83]
	v_mfma_f32_16x16x32_bf16 v[68:71], v[206:209], v[198:201], v[68:71]
	v_mfma_f32_16x16x32_bf16 v[64:67], v[214:217], v[198:201], v[64:67]
	s_mov_b32 m0, s96
	v_lshl_add_u64 v[180:181], v[220:221], 0, s[52:53]
	s_barrier
	ds_read_b128 v[160:163], v186 offset:49152
	ds_read_b128 v[164:167], v186 offset:50176
	ds_read_b128 v[168:171], v186 offset:51200
	ds_read_b128 v[172:175], v186 offset:52224
	ds_read_b128 v[176:179], v186 offset:53248
	ds_read_b128 v[190:193], v186 offset:54272
	ds_read_b128 v[194:197], v186 offset:55296
	ds_read_b128 v[198:201], v186 offset:56320
	global_load_lds_dwordx4 v[180:181], off
	v_lshl_add_u64 v[180:181], v[222:223], 0, s[52:53]
	s_mov_b32 m0, s97
	s_nop 0
	global_load_lds_dwordx4 v[180:181], off
	s_barrier
; __device__ __forceinline__ void st_bf16x8(bf16_t* p, const f32x4 a, const f32x4 b) { uint4 o; o.x = cvt_pk_bf16(a[0], a[1]); o.y = cvt_pk_bf16(a[2], a[3]); o.z = cvt_pk_bf16(b[0], b[1]); o.w = cvt_pk_bf16(b[2], b[3]); *(uint4*)p = o; }
; #define PG8_STAGE(bufoff, gbase, voff) do { _Pragma("unroll") for (int _i = 0; _i < 2; ++_i) \
;         __builtin_amdgcn_global_load_lds((const unsigned*)((const char*)(gbase) + (voff)[_i]), (LAS unsigned*)(lds + (bufoff) + ldsw + _i * 8192), 16, 0, 0); } while (0)
; #define PG8_WAIT_V(n) asm volatile("s_waitcnt vmcnt(" #n ")" ::: "memory")
; #define PG8_WAIT_L(n) asm volatile("s_waitcnt lgkmcnt(" #n ")" ::: "memory")
; #define PG8_BAR __builtin_amdgcn_s_barrier()
; #define PG8_SCHED __builtin_amdgcn_sched_barrier(0)
;     __device__ __forceinline__ void row(const f32x4 (&a)[2][2], int row, int pn, int wc, int fq) const {
;     ...
;             for (int bj = 0; bj < 2; ++bj) { const int d = head * 64 + bj * 32 + 8 * fq;
;                 const f32x4 v0 = g[bj][0] * rs * *(const f32x4*)(g_v + d), v1 = g[bj][1] * rs * *(const f32x4*)(g_v + d + 4);
;                 st_bf16x8(pV + (size_t)row * 512 + d, v0, v1);
;                 if (row >= NP && row < NTOK) { float* o = out + O_VS + (size_t)(row - NP) * 512 + d; *(f32x4*)o = v0; *(f32x4*)(o + 4) = v1; } }
;         } else {
;             const int c = (pn - 6) * 128 + wc * 32 + 8 * fq;
;             const f32x4 z0 = a[0][0] * a[1][0], z1 = a[0][1] * a[1][1];
;             st_bf16x8(pZ + (size_t)row * 512 + c, z0, z1);
;             float* o = nullptr;
;             if (row < NP) { const int t = row & 2047; if (t >= 2046) o = out + O_CONVP + (size_t)((row >> 11) * 2 + (t - 2046)) * 512 + c; }
;             else if (row < NTOK) o = out + O_CONVS + (size_t)((row - NP) * 2 + 1) * 512 + c;
;             if (o) { *(f32x4*)o = z0; *(f32x4*)(o + 4) = z1; }
; template <class Epi>
; __device__ __forceinline__ void gemm_phase(LAS unsigned char* lds, const Gemm g, const StaticOrder& S, const Epi& E, float* smem = nullptr) {
;     ...
;             PG8_BAR; PG8_WAIT_L(0); PG8_MMA(1, 0, At, B0); PG8_BAR; PG8_SCHED;
;             PG8_STAGE(PG8_SB(1, 1), b3 + hstep, voffA);
;             PG8_WAIT_V(6); PG8_BAR; PG8_MMA(1, 1, At, B1); PG8_BAR;
;         }
;         if constexpr (!Epi::AFTER_DRAIN) E(acc, cur, wr, wc, fr, fq);
	s_waitcnt lgkmcnt(0)
	s_waitcnt lgkmcnt(0)
	v_mfma_f32_16x16x32_bf16 v[60:63], v[128:131], v[160:163], v[60:63]
	v_mfma_f32_16x16x32_bf16 v[56:59], v[152:155], v[160:163], v[56:59]
	v_mfma_f32_16x16x32_bf16 v[44:47], v[128:131], v[168:171], v[44:47]
	v_mfma_f32_16x16x32_bf16 v[40:43], v[152:155], v[168:171], v[40:43]
	v_mfma_f32_16x16x32_bf16 v[28:31], v[128:131], v[176:179], v[28:31]
	v_mfma_f32_16x16x32_bf16 v[24:27], v[152:155], v[176:179], v[24:27]
	v_mfma_f32_16x16x32_bf16 v[12:15], v[128:131], v[194:197], v[12:15]
	v_mfma_f32_16x16x32_bf16 v[8:11], v[152:155], v[194:197], v[8:11]
	v_mfma_f32_16x16x32_bf16 v[60:63], v[132:135], v[164:167], v[60:63]
	v_mfma_f32_16x16x32_bf16 v[56:59], v[156:159], v[164:167], v[56:59]
	v_mfma_f32_16x16x32_bf16 v[44:47], v[132:135], v[172:175], v[44:47]
	v_mfma_f32_16x16x32_bf16 v[40:43], v[156:159], v[172:175], v[40:43]
	v_mfma_f32_16x16x32_bf16 v[28:31], v[132:135], v[190:193], v[28:31]
	v_mfma_f32_16x16x32_bf16 v[24:27], v[156:159], v[190:193], v[24:27]
	v_mfma_f32_16x16x32_bf16 v[12:15], v[132:135], v[198:201], v[12:15]
	v_mfma_f32_16x16x32_bf16 v[8:11], v[156:159], v[198:201], v[8:11]
	s_barrier
	s_add_u32 s8, s8, 0x40080
	s_addc_u32 s9, s9, 0
	s_add_i32 s10, s10, s85
	v_lshl_add_u64 v[128:129], s[8:9], 0, v[136:137]
	s_mov_b32 m0, s10
	s_nop 0
	global_load_lds_dwordx4 v[128:129], off
	v_lshl_add_u64 v[128:129], s[8:9], 0, v[138:139]
	s_add_i32 m0, s10, 0x2000
	s_nop 0
	global_load_lds_dwordx4 v[128:129], off
	s_waitcnt vmcnt(6)
	s_barrier
	v_mfma_f32_16x16x32_bf16 v[52:55], v[202:205], v[160:163], v[52:55]
	v_mfma_f32_16x16x32_bf16 v[48:51], v[210:213], v[160:163], v[48:51]
	v_mfma_f32_16x16x32_bf16 v[36:39], v[202:205], v[168:171], v[36:39]
	v_mfma_f32_16x16x32_bf16 v[32:35], v[210:213], v[168:171], v[32:35]
	v_mfma_f32_16x16x32_bf16 v[20:23], v[202:205], v[176:179], v[20:23]
	v_mfma_f32_16x16x32_bf16 v[16:19], v[210:213], v[176:179], v[16:19]
	v_mfma_f32_16x16x32_bf16 v[4:7], v[202:205], v[194:197], v[4:7]
	v_mfma_f32_16x16x32_bf16 v[0:3], v[210:213], v[194:197], v[0:3]
	v_mfma_f32_16x16x32_bf16 v[52:55], v[206:209], v[164:167], v[52:55]
	v_mfma_f32_16x16x32_bf16 v[48:51], v[214:217], v[164:167], v[48:51]
	v_mfma_f32_16x16x32_bf16 v[36:39], v[206:209], v[172:175], v[36:39]
	v_mfma_f32_16x16x32_bf16 v[32:35], v[214:217], v[172:175], v[32:35]
	v_mfma_f32_16x16x32_bf16 v[20:23], v[206:209], v[190:193], v[20:23]
	v_mfma_f32_16x16x32_bf16 v[16:19], v[214:217], v[190:193], v[16:19]
	v_mfma_f32_16x16x32_bf16 v[4:7], v[206:209], v[198:201], v[4:7]
	v_mfma_f32_16x16x32_bf16 v[0:3], v[214:217], v[198:201], v[0:3]
	s_add_i32 s80, s80, 2
	s_add_u32 s6, s6, 0x100
	s_addc_u32 s7, s7, 0
	s_add_u32 s73, s73, 0x100
	s_addc_u32 s75, s75, 0
	s_cmp_gt_u32 s80, 13
	s_barrier
	s_cbranch_scc0 .LBB0_212
	s_lshl_b32 s73, s4, 8
	s_add_i32 s73, s73, s90
	s_cmp_lt_i32 s0, 2
	s_cselect_b64 s[80:81], -1, 0
	s_cmp_gt_i32 s0, 1
	s_cselect_b64 s[4:5], -1, 0
	s_and_b32 s1, s0, -2
	s_cmp_lg_u32 s1, 4
	s_cselect_b64 s[6:7], -1, 0
	s_and_b64 s[6:7], s[4:5], s[6:7]
	s_cmp_gt_u32 s0, 3
	s_cselect_b64 s[82:83], -1, 0
	s_lshl_b32 s4, s0, 8
	s_and_b32 s75, s73, 0xffffff80
	v_lshl_add_u32 v154, s0, 7, v183
	v_add_u32_e32 v140, s4, v184
	s_cmpk_eq_i32 s75, 0x4000
	v_or_b32_e32 v156, s73, v143
	v_ashrrev_i32_e32 v155, 31, v154
	v_or_b32_e32 v152, 32, v140
	v_mov_b32_e32 v153, v141
	s_mov_b64 s[0:1], -1
	s_cselect_b64 s[10:11], -1, 0
	s_andn2_b64 s[98:99], s[6:7], s[82:83]
	s_and_b64 vcc, exec, s[98:99]
	s_cbranch_vccz .Lgv_nobp
	v_lshlrev_b32_e32 v220, 2, v142
	ds_bpermute_b32 v204, v220, v241
	ds_bpermute_b32 v205, v220, v241 offset:4
	ds_bpermute_b32 v206, v220, v241 offset:8
	ds_bpermute_b32 v207, v220, v241 offset:12
	ds_bpermute_b32 v208, v220, v241 offset:16
	ds_bpermute_b32 v209, v220, v241 offset:20
	ds_bpermute_b32 v210, v220, v241 offset:24
	ds_bpermute_b32 v211, v220, v241 offset:28
	ds_bpermute_b32 v212, v220, v241 offset:128
	ds_bpermute_b32 v213, v220, v241 offset:132
	ds_bpermute_b32 v214, v220, v241 offset:136
	ds_bpermute_b32 v215, v220, v241 offset:140
	ds_bpermute_b32 v216, v220, v241 offset:144
	ds_bpermute_b32 v217, v220, v241 offset:148
	ds_bpermute_b32 v218, v220, v241 offset:152
	ds_bpermute_b32 v219, v220, v241 offset:156
.Lgv_nobp:
	s_and_b64 vcc, exec, s[6:7]
	s_cbranch_vccz .LBB0_224
	s_and_b64 vcc, exec, s[82:83]
	s_cbranch_vccz .LBB0_218
	v_ashrrev_i32_e32 v157, 31, v156
	v_lshlrev_b64 v[158:159], 10, v[156:157]
	s_cmpk_lt_u32 s73, 0x4080
	v_lshl_add_u64 v[158:159], s[50:51], 0, v[158:159]
	v_cmp_lt_i32_e32 vcc, s12, v156
	s_cselect_b64 s[0:1], -1, 0
	v_pk_mul_f32 v[130:131], v[126:127], v[118:119]
	v_pk_mul_f32 v[128:129], v[124:125], v[116:117]
	v_pk_mul_f32 v[134:135], v[122:123], v[114:115]
	v_pk_mul_f32 v[132:133], v[120:121], v[112:113]
	v_lshl_add_u64 v[162:163], v[154:155], 1, v[158:159]
	s_and_b64 s[8:9], s[0:1], vcc
	v_cvt_pk_bf16_f32 v158, v128, v129
	v_cvt_pk_bf16_f32 v159, v130, v131
	v_cvt_pk_bf16_f32 v160, v132, v133
	v_cvt_pk_bf16_f32 v161, v134, v135
	global_store_dwordx4 v[162:163], v[158:161], off
	s_and_saveexec_b64 s[0:1], s[8:9]
	s_cbranch_execz .LBB0_217
	v_lshl_add_u32 v158, v156, 1, v189
	v_mov_b32_e32 v159, v141
	v_lshlrev_b64 v[158:159], 11, v[158:159]
	v_lshl_add_u64 v[158:159], s[66:67], 0, v[158:159]
	v_lshl_add_u64 v[158:159], v[154:155], 2, v[158:159]
	global_store_dwordx4 v[158:159], v[128:131], off
	global_store_dwordx4 v[158:159], v[132:135], off offset:16

; __device__ __forceinline__ float gelu_tanh(float x) { const float u = 1.5957691216f * (x + 0.044715f * x * x * x); return x * __builtin_amdgcn_rcpf(1.f + __expf(-u)); }
; __device__ __forceinline__ void st_bf16x8(bf16_t* p, const f32x4 a, const f32x4 b) { uint4 o; o.x = cvt_pk_bf16(a[0], a[1]); o.y = cvt_pk_bf16(a[2], a[3]); o.z = cvt_pk_bf16(b[0], b[1]); o.w = cvt_pk_bf16(b[2], b[3]); *(uint4*)p = o; }
;     __device__ __forceinline__ void row(const f32x4 (&a)[2][2], int row, int pn, int wc, int fq) const {
;     ...
;             const int head = (pn - 2) * 4 + wc;
;             f32x4 g[2][2]; float ss = 0.f;
; #pragma unroll
;             for (int bj = 0; bj < 2; ++bj)
; #pragma unroll
;                 for (int n = 0; n < 2; ++n)
; #pragma unroll
;                     for (int j = 0; j < 4; ++j) { const float t = gelu_tanh(a[bj][n][j]); g[bj][n][j] = t; ss += t * t; }
;             ss += __shfl_xor(ss, 16); ss += __shfl_xor(ss, 32);
;             const float rs = rsqrtf(ss * (1.f / 64.f) + EPS);
; #pragma unroll
;             for (int bj = 0; bj < 2; ++bj) { const int d = head * 64 + bj * 32 + 8 * fq;
;                 const f32x4 v0 = g[bj][0] * rs * *(const f32x4*)(g_v + d), v1 = g[bj][1] * rs * *(const f32x4*)(g_v + d + 4);
;                 st_bf16x8(pV + (size_t)row * 512 + d, v0, v1);
.LBB0_218:
	s_andn2_b64 vcc, exec, s[0:1]
	s_cbranch_vccnz .LBB0_223
	v_mov_b32_e32 v190, 0x3d372713
	v_mov_b32_e32 v192, 0xbfcc422a
	v_mov_b32_e32 v194, 0x3fb8aa3b
	v_pk_mul_f32 v[128:129], v[124:125], v[190:191] op_sel_hi:[1,0]
	v_pk_mul_f32 v[132:133], v[126:127], v[190:191] op_sel_hi:[1,0]
	v_pk_mul_f32 v[158:159], v[120:121], v[190:191] op_sel_hi:[1,0]
	v_pk_mul_f32 v[160:161], v[122:123], v[190:191] op_sel_hi:[1,0]
	v_pk_mul_f32 v[162:163], v[116:117], v[190:191] op_sel_hi:[1,0]
	v_pk_mul_f32 v[164:165], v[118:119], v[190:191] op_sel_hi:[1,0]
	v_pk_mul_f32 v[166:167], v[112:113], v[190:191] op_sel_hi:[1,0]
	v_pk_mul_f32 v[168:169], v[114:115], v[190:191] op_sel_hi:[1,0]
	v_pk_mul_f32 v[128:129], v[124:125], v[128:129]
	v_pk_mul_f32 v[132:133], v[126:127], v[132:133]
	v_pk_mul_f32 v[158:159], v[120:121], v[158:159]
	v_pk_mul_f32 v[160:161], v[122:123], v[160:161]
	v_pk_mul_f32 v[162:163], v[116:117], v[162:163]
	v_pk_mul_f32 v[164:165], v[118:119], v[164:165]
	v_pk_mul_f32 v[166:167], v[112:113], v[166:167]
	v_pk_mul_f32 v[168:169], v[114:115], v[168:169]
	v_pk_fma_f32 v[128:129], v[124:125], v[128:129], v[124:125]
	v_pk_fma_f32 v[132:133], v[126:127], v[132:133], v[126:127]
	v_pk_fma_f32 v[158:159], v[120:121], v[158:159], v[120:121]
	v_pk_fma_f32 v[160:161], v[122:123], v[160:161], v[122:123]
	v_pk_fma_f32 v[162:163], v[116:117], v[162:163], v[116:117]
	v_pk_fma_f32 v[164:165], v[118:119], v[164:165], v[118:119]
	v_pk_fma_f32 v[166:167], v[112:113], v[166:167], v[112:113]
	v_pk_fma_f32 v[168:169], v[114:115], v[168:169], v[114:115]
	v_pk_mul_f32 v[128:129], v[128:129], v[192:193] op_sel_hi:[1,0]
	v_pk_mul_f32 v[132:133], v[132:133], v[192:193] op_sel_hi:[1,0]
	v_pk_mul_f32 v[158:159], v[158:159], v[192:193] op_sel_hi:[1,0]
	v_pk_mul_f32 v[160:161], v[160:161], v[192:193] op_sel_hi:[1,0]
	v_pk_mul_f32 v[162:163], v[162:163], v[192:193] op_sel_hi:[1,0]
	v_pk_mul_f32 v[164:165], v[164:165], v[192:193] op_sel_hi:[1,0]
	v_pk_mul_f32 v[166:167], v[166:167], v[192:193] op_sel_hi:[1,0]
	v_pk_mul_f32 v[168:169], v[168:169], v[192:193] op_sel_hi:[1,0]
	v_pk_mul_f32 v[128:129], v[128:129], v[194:195] op_sel_hi:[1,0]
	v_pk_mul_f32 v[132:133], v[132:133], v[194:195] op_sel_hi:[1,0]
	v_pk_mul_f32 v[158:159], v[158:159], v[194:195] op_sel_hi:[1,0]
	v_pk_mul_f32 v[160:161], v[160:161], v[194:195] op_sel_hi:[1,0]
	v_pk_mul_f32 v[162:163], v[162:163], v[194:195] op_sel_hi:[1,0]
	v_pk_mul_f32 v[164:165], v[164:165], v[194:195] op_sel_hi:[1,0]
	v_pk_mul_f32 v[166:167], v[166:167], v[194:195] op_sel_hi:[1,0]
	v_pk_mul_f32 v[168:169], v[168:169], v[194:195] op_sel_hi:[1,0]
	v_exp_f32_e32 v128, v128
	v_exp_f32_e32 v129, v129
	v_exp_f32_e32 v132, v132
	v_exp_f32_e32 v133, v133
	v_exp_f32_e32 v158, v158
	v_exp_f32_e32 v159, v159
	v_exp_f32_e32 v160, v160
	v_exp_f32_e32 v161, v161
	v_exp_f32_e32 v162, v162
	v_exp_f32_e32 v163, v163
	v_exp_f32_e32 v164, v164
	v_exp_f32_e32 v165, v165
	v_exp_f32_e32 v166, v166
	v_exp_f32_e32 v167, v167
	v_exp_f32_e32 v168, v168
	v_exp_f32_e32 v169, v169
	v_pk_add_f32 v[128:129], v[128:129], 1.0 op_sel_hi:[1,0]
	v_pk_add_f32 v[132:133], v[132:133], 1.0 op_sel_hi:[1,0]
	v_pk_add_f32 v[158:159], v[158:159], 1.0 op_sel_hi:[1,0]
	v_pk_add_f32 v[160:161], v[160:161], 1.0 op_sel_hi:[1,0]
	v_pk_add_f32 v[162:163], v[162:163], 1.0 op_sel_hi:[1,0]
	v_pk_add_f32 v[164:165], v[164:165], 1.0 op_sel_hi:[1,0]
	v_pk_add_f32 v[166:167], v[166:167], 1.0 op_sel_hi:[1,0]
	v_pk_add_f32 v[168:169], v[168:169], 1.0 op_sel_hi:[1,0]
	v_rcp_f32_e32 v128, v128
	v_rcp_f32_e32 v129, v129
	v_rcp_f32_e32 v132, v132
	v_rcp_f32_e32 v133, v133
	v_rcp_f32_e32 v158, v158
	v_rcp_f32_e32 v159, v159
	v_rcp_f32_e32 v160, v160
	v_rcp_f32_e32 v161, v161
	v_rcp_f32_e32 v162, v162
	v_rcp_f32_e32 v163, v163
	v_rcp_f32_e32 v164, v164
	v_rcp_f32_e32 v165, v165
	v_rcp_f32_e32 v166, v166
	v_rcp_f32_e32 v167, v167
	v_rcp_f32_e32 v168, v168
	v_rcp_f32_e32 v169, v169
	v_pk_mul_f32 v[128:129], v[124:125], v[128:129]
	v_pk_mul_f32 v[132:133], v[126:127], v[132:133]
	v_pk_mul_f32 v[158:159], v[120:121], v[158:159]
	v_pk_mul_f32 v[160:161], v[122:123], v[160:161]
	v_pk_mul_f32 v[162:163], v[116:117], v[162:163]
	v_pk_mul_f32 v[164:165], v[118:119], v[164:165]
	v_pk_mul_f32 v[166:167], v[112:113], v[166:167]
	v_pk_mul_f32 v[168:169], v[114:115], v[168:169]
	v_pk_mul_f32 v[130:131], v[128:129], v[128:129]
	v_pk_mul_f32 v[134:135], v[132:133], v[132:133]
	v_add_f32_e32 v130, v130, v131
	v_add_f32_e32 v130, v134, v130
	v_pk_mul_f32 v[170:171], v[158:159], v[158:159]
	v_add_f32_e32 v130, v135, v130
	v_add_f32_e32 v130, v170, v130
	v_pk_mul_f32 v[172:173], v[160:161], v[160:161]
	v_add_f32_e32 v130, v171, v130
	v_add_f32_e32 v130, v172, v130
	v_pk_mul_f32 v[174:175], v[162:163], v[162:163]
	v_add_f32_e32 v130, v173, v130
	v_add_f32_e32 v130, v130, v174
	v_pk_mul_f32 v[176:177], v[164:165], v[164:165]
	v_add_f32_e32 v130, v175, v130
	v_add_f32_e32 v130, v176, v130
	v_pk_mul_f32 v[178:179], v[166:167], v[166:167]
	v_add_f32_e32 v130, v177, v130
	v_add_f32_e32 v130, v178, v130
	v_pk_mul_f32 v[180:181], v[168:169], v[168:169]
	v_add_f32_e32 v130, v179, v130
	v_add_f32_e32 v130, v180, v130
	v_add_f32_e32 v130, v181, v130
	ds_bpermute_b32 v131, v229, v130
	v_lshl_add_u64 v[180:181], v[140:141], 2, s[18:19]
	v_ashrrev_i32_e32 v157, 31, v156
	v_lshlrev_b64 v[174:175], 10, v[156:157]
	v_lshlrev_b32_e32 v172, 9, v156
	s_waitcnt lgkmcnt(0)
	v_add_f32_e32 v130, v130, v131
	ds_bpermute_b32 v131, v230, v130
	v_mov_b32_e32 v173, v141
	v_cndmask_b32_e64 v157, 0, 1, s[10:11]
	v_cmp_ne_u32_e64 s[0:1], 1, v157
	s_waitcnt lgkmcnt(0)
	v_add_f32_e32 v130, v130, v131
	v_fmamk_f32 v130, v130, 0x3c800000, v188
	v_cmp_gt_f32_e32 vcc, s13, v130
	v_mul_f32_e32 v131, 0x4b800000, v130
	s_nop 0
	v_cndmask_b32_e32 v130, v130, v131, vcc
	v_rsq_f32_e32 v130, v130
	s_nop 0
	v_mul_f32_e32 v131, 0x45800000, v130
	v_cndmask_b32_e32 v170, v130, v131, vcc
	v_pk_mul_f32 v[176:177], v[128:129], v[170:171] op_sel_hi:[1,0]
	v_pk_mul_f32 v[178:179], v[132:133], v[170:171] op_sel_hi:[1,0]
	s_waitcnt lgkmcnt(0)
	v_mov_b64_e32 v[128:129], v[208:209]
	v_mov_b64_e32 v[130:131], v[210:211]
	v_mov_b64_e32 v[132:133], v[204:205]
	v_mov_b64_e32 v[134:135], v[206:207]
	v_pk_mul_f32 v[158:159], v[158:159], v[170:171] op_sel_hi:[1,0]
	v_pk_mul_f32 v[160:161], v[160:161], v[170:171] op_sel_hi:[1,0]
	s_andn2_b64 vcc, exec, s[10:11]
	v_pk_mul_f32 v[128:129], v[128:129], v[158:159]
	v_lshl_add_u64 v[158:159], s[46:47], 0, v[174:175]
	v_pk_mul_f32 v[134:135], v[134:135], v[178:179]
	v_pk_mul_f32 v[132:133], v[132:133], v[176:177]
	v_pk_mul_f32 v[130:131], v[130:131], v[160:161]
	v_lshl_add_u64 v[158:159], v[140:141], 1, v[158:159]
	v_lshl_add_u64 v[160:161], v[172:173], 2, s[56:57]
	v_cvt_pk_bf16_f32 v174, v132, v133
	v_cvt_pk_bf16_f32 v175, v134, v135
	v_cvt_pk_bf16_f32 v176, v128, v129
	v_cvt_pk_bf16_f32 v177, v130, v131
	v_mov_b64_e32 v[196:197], v[174:175]
	v_mov_b64_e32 v[198:199], v[176:177]
	s_cbranch_vccnz .LBB0_221
;     __device__ __forceinline__ void row(const f32x4 (&a)[2][2], int row, int pn, int wc, int fq) const {
;     ...
;                 if (row >= NP && row < NTOK) { float* o = out + O_VS + (size_t)(row - NP) * 512 + d; *(f32x4*)o = v0; *(f32x4*)(o + 4) = v1; } }
	v_lshl_add_u64 v[172:173], v[140:141], 2, v[160:161]
	v_lshl_add_u64 v[174:175], v[172:173], 0, s[70:71]
	v_add_co_u32_e32 v172, vcc, 0x2108000, v172
	s_nop 1
	v_addc_co_u32_e32 v173, vcc, 0, v173, vcc
	global_store_dwordx4 v[172:173], v[132:135], off
	global_store_dwordx4 v[174:175], v[128:131], off offset:16

; __global__ __launch_bounds__(512, 2) void fwd_megakernel(Params p) {
	.amdhsa_kernel _Z14fwd_megakernel6Params
		.amdhsa_group_segment_fixed_size 16
		.amdhsa_private_segment_fixed_size 0
		.amdhsa_kernarg_size 424
		.amdhsa_user_sgpr_count 2
		.amdhsa_user_sgpr_dispatch_ptr 0
		.amdhsa_user_sgpr_queue_ptr 0
		.amdhsa_user_sgpr_kernarg_segment_ptr 1
		.amdhsa_user_sgpr_dispatch_id 0
		.amdhsa_user_sgpr_kernarg_preload_length 0
		.amdhsa_user_sgpr_kernarg_preload_offset 0
		.amdhsa_user_sgpr_private_segment_size 0
		.amdhsa_uses_dynamic_stack 0
		.amdhsa_enable_private_segment 0
		.amdhsa_system_sgpr_workgroup_id_x 1
		.amdhsa_system_sgpr_workgroup_id_y 0
		.amdhsa_system_sgpr_workgroup_id_z 0
		.amdhsa_system_sgpr_workgroup_info 0
		.amdhsa_system_vgpr_workitem_id 2
		.amdhsa_next_free_vgpr 242
		.amdhsa_next_free_sgpr 102
		.amdhsa_accum_offset 244
		.amdhsa_reserve_vcc 1
		.amdhsa_float_round_mode_32 0
		.amdhsa_float_round_mode_16_64 0
		.amdhsa_float_denorm_mode_32 3
		.amdhsa_float_denorm_mode_16_64 3
		.amdhsa_dx10_clamp 1
		.amdhsa_ieee_mode 1
		.amdhsa_fp16_overflow 0
		.amdhsa_tg_split 0
		.amdhsa_exception_fp_ieee_invalid_op 0
		.amdhsa_exception_fp_denorm_src 0
		.amdhsa_exception_fp_ieee_div_zero 0
		.amdhsa_exception_fp_ieee_overflow 0
		.amdhsa_exception_fp_ieee_underflow 0
		.amdhsa_exception_fp_ieee_inexact 0
		.amdhsa_exception_int_div_zero 0
	.end_amdhsa_kernel

; __global__ __launch_bounds__(512, 2) void fwd_megakernel(Params p) {
.Lfunc_end0:
	.size	_Z14fwd_megakernel6Params, .Lfunc_end0-_Z14fwd_megakernel6Params
	.set _Z14fwd_megakernel6Params.num_vgpr, 242
	.set _Z14fwd_megakernel6Params.num_agpr, 0
	.set _Z14fwd_megakernel6Params.numbered_sgpr, 98
	.set _Z14fwd_megakernel6Params.num_named_barrier, 0
	.set _Z14fwd_megakernel6Params.private_seg_size, 0
	.set _Z14fwd_megakernel6Params.uses_vcc, 1
	.set _Z14fwd_megakernel6Params.uses_flat_scratch, 0
	.set _Z14fwd_megakernel6Params.has_dyn_sized_stack, 0
	.set _Z14fwd_megakernel6Params.has_recursion, 0
	.set _Z14fwd_megakernel6Params.has_indirect_call, 0

; __global__ __launch_bounds__(512, 2) void fwd_megakernel(Params p) {
amdhsa.kernels:
  - .agpr_count:     0
    .args:
      - .offset:         0
        .size:           168
        .value_kind:     by_value
      - .offset:         168
        .size:           4
        .value_kind:     hidden_block_count_x
      - .offset:         172
        .size:           4
        .value_kind:     hidden_block_count_y
      - .offset:         176
        .size:           4
        .value_kind:     hidden_block_count_z
      - .offset:         180
        .size:           2
        .value_kind:     hidden_group_size_x
      - .offset:         182
        .size:           2
        .value_kind:     hidden_group_size_y
      - .offset:         184
        .size:           2
        .value_kind:     hidden_group_size_z
      - .offset:         186
        .size:           2
        .value_kind:     hidden_remainder_x
      - .offset:         188
        .size:           2
        .value_kind:     hidden_remainder_y
      - .offset:         190
        .size:           2
        .value_kind:     hidden_remainder_z
      - .offset:         208
        .size:           8
        .value_kind:     hidden_global_offset_x
      - .offset:         216
        .size:           8
        .value_kind:     hidden_global_offset_y
      - .offset:         224
        .size:           8
        .value_kind:     hidden_global_offset_z
      - .offset:         232
        .size:           2
        .value_kind:     hidden_grid_dims
      - .offset:         256
        .size:           8
        .value_kind:     hidden_multigrid_sync_arg
      - .offset:         288
        .size:           4
        .value_kind:     hidden_dynamic_lds_size
    .group_segment_fixed_size: 16
    .kernarg_segment_align: 8
    .kernarg_segment_size: 424
    .language:       OpenCL C
    .language_version:
      - 2
      - 0
    .max_flat_workgroup_size: 512
    .name:           _Z14fwd_megakernel6Params
    .private_segment_fixed_size: 0
    .sgpr_count:     108
    .sgpr_spill_count: 9
    .symbol:         _Z14fwd_megakernel6Params.kd
    .uniform_work_group_size: 1
    .uses_dynamic_stack: false
    .vgpr_count:     242
    .vgpr_spill_count: 0
    .wavefront_size: 64
